# v95 stack + P4 softmax epilogue: store addresses of row blocks 1..7 derived from block 0 by a constant 64-bit add instead of the 7-instruction recomputation per block
# speedup vs baseline: 1.0004x; 1.0004x over previous
; __device__ __forceinline__ u32x4 pack8(f32x4 v0, f32x4 v1) { u32x4 w; w.x = cvt_pk_bf16(v0[0], v0[1]); w.y = cvt_pk_bf16(v0[2], v0[3]); w.z = cvt_pk_bf16(v1[0], v1[1]); w.w = cvt_pk_bf16(v1[2], v1[3]); return w; }
;     __device__ __forceinline__ void operator()(Acc& acc, const Unit& u, int wr, int wc, int fr, int fq, PG8_LAS unsigned char* xl) const {
;     ...
;             for (int m = 0; m < 4; ++m) { const int rl = ai * HALF + wr * 64 + m * 16 + fr;
;                 const f32x2 a = X[rl * 4 + 0], b = X[rl * 4 + 1], c = X[rl * 4 + 2], d = X[rl * 4 + 3];
;                 const float M = fmaxf(fmaxf(a.x, b.x), fmaxf(c.x, d.x));
;                 const float tot = a.y * __builtin_amdgcn_exp2f(a.x - M) + b.y * __builtin_amdgcn_exp2f(b.x - M) + c.y * __builtin_amdgcn_exp2f(c.x - M) + d.y * __builtin_amdgcn_exp2f(d.x - M);
;                 const float own = wc == 0 ? a.x : wc == 1 ? b.x : wc == 2 ? c.x : d.x;
;                 const float f = __builtin_amdgcn_exp2f(own - M) / tot;
;                 bf16_t* rowp = P + (size_t)(u.r0 + rl) * ldc + u.c0 + wc * 32 + 8 * fq;
; #pragma unroll
;                 for (int bj = 0; bj < 2; ++bj) *(u32x4*)(rowp + bj * HALF) = pack8(acc[ai][bj][m][0] * f, acc[ai][bj][m][1] * f); }
.LBB0_603:
	v_sub_f32_e32 v0, v0, v188
	v_exp_f32_e32 v0, v0
	v_sub_f32_e32 v2, v2, v188
	v_exp_f32_e32 v2, v2
	v_mul_f32_e32 v6, v7, v6
	v_fmac_f32_e32 v6, v5, v187
	v_fmac_f32_e32 v6, v1, v0
	v_fmac_f32_e32 v6, v3, v2
	v_div_scale_f32 v0, s[2:3], v6, v6, v4
	v_rcp_f32_e32 v1, v0
	s_ashr_i32 s13, s12, 31
	s_cmp_lt_i32 s64, 1
	v_fma_f32 v2, -v0, v1, 1.0
	v_fmac_f32_e32 v1, v2, v1
	v_div_scale_f32 v2, vcc, v4, v6, v4
	v_mul_f32_e32 v3, v2, v1
	v_fma_f32 v5, -v0, v3, v2
	v_fmac_f32_e32 v3, v5, v1
	v_fma_f32 v0, -v0, v3, v2
	v_div_fmas_f32 v0, v0, v1, v3
	v_div_fixup_f32 v4, v0, v6, v4
	s_mov_b32 s88, 0x8000
	s_mov_b32 s89, 0
	s_mov_b32 s90, 0x28000
	s_mov_b32 s91, 0
	v_add_u32_e32 v0, s58, v155
	v_ashrrev_i32_e32 v1, 31, v0
	v_lshlrev_b64 v[0:1], 11, v[0:1]
	v_lshl_add_u64 v[0:1], s[16:17], 0, v[0:1]
	v_lshl_add_u64 v[0:1], s[12:13], 1, v[0:1]
	v_lshl_add_u64 v[0:1], v[0:1], 0, s[22:23]
	v_lshl_add_u64 v[6:7], v[0:1], 0, v[136:137]
	v_pk_mul_f32 v[0:1], v[120:121], v[4:5] op_sel_hi:[1,0]
	v_pk_mul_f32 v[2:3], v[126:127], v[4:5] op_sel_hi:[1,0]
	v_cvt_pk_bf16_f32 v0, v0, v1
	v_pk_mul_f32 v[120:121], v[150:151], v[4:5] op_sel_hi:[1,0]
	v_cvt_pk_bf16_f32 v1, v2, v3
	v_pk_mul_f32 v[124:125], v[124:125], v[4:5] op_sel_hi:[1,0]
	s_nop 0
	v_cvt_pk_bf16_f32 v2, v124, v125
	v_cvt_pk_bf16_f32 v3, v120, v121
	flat_store_dwordx4 v[6:7], v[0:3]
	v_pk_mul_f32 v[120:121], v[152:153], v[4:5] op_sel_hi:[1,0]
	s_nop 0
	v_pk_mul_f32 v[0:1], v[122:123], v[4:5] op_sel_hi:[1,0]
	v_pk_mul_f32 v[2:3], v[148:149], v[4:5] op_sel_hi:[1,0]
	v_cvt_pk_bf16_f32 v0, v0, v1
	v_pk_mul_f32 v[4:5], v[146:147], v[4:5] op_sel_hi:[1,0]
	v_cvt_pk_bf16_f32 v1, v2, v3
	s_nop 0
	v_cvt_pk_bf16_f32 v2, v4, v5
	v_cvt_pk_bf16_f32 v3, v120, v121
	flat_store_dwordx4 v[6:7], v[0:3] offset:256
	v_mov_b64_e32 v[126:127], v[6:7]
	s_nop 1
	v_add_u32_e32 v0, 0, v161
	v_add_u32_e32 v4, 0x20000, v0
	ds_read_b128 v[0:3], v4 offset:16
	ds_read_b128 v[4:7], v4
	s_waitcnt lgkmcnt(0)
	v_max_f32_e32 v120, v2, v2
	v_max_f32_e32 v121, v0, v0
	v_max_f32_e32 v120, v121, v120
	v_max3_f32 v121, v4, v6, v120
	v_sub_f32_e32 v4, v4, v121
	v_exp_f32_e32 v120, v4
	v_sub_f32_e32 v4, v6, v121
	v_exp_f32_e32 v6, v4
	v_mov_b32_e32 v4, v120
	s_cbranch_scc1 .LBB0_608
	s_cmp_lg_u32 s64, 1
	s_mov_b64 s[2:3], -1
	s_cbranch_scc0 .LBB0_606
	v_cndmask_b32_e64 v4, v2, v0, s[8:9]
	v_sub_f32_e32 v4, v4, v121
	v_exp_f32_e32 v4, v4
	s_mov_b64 s[2:3], 0

; __device__ __forceinline__ u32x4 pack8(f32x4 v0, f32x4 v1) { u32x4 w; w.x = cvt_pk_bf16(v0[0], v0[1]); w.y = cvt_pk_bf16(v0[2], v0[3]); w.z = cvt_pk_bf16(v1[0], v1[1]); w.w = cvt_pk_bf16(v1[2], v1[3]); return w; }
;     __device__ __forceinline__ void operator()(Acc& acc, const Unit& u, int wr, int wc, int fr, int fq, PG8_LAS unsigned char* xl) const {
;     ...
;             for (int m = 0; m < 4; ++m) { const int rl = ai * HALF + wr * 64 + m * 16 + fr;
;                 const f32x2 a = X[rl * 4 + 0], b = X[rl * 4 + 1], c = X[rl * 4 + 2], d = X[rl * 4 + 3];
;                 const float M = fmaxf(fmaxf(a.x, b.x), fmaxf(c.x, d.x));
;                 const float tot = a.y * __builtin_amdgcn_exp2f(a.x - M) + b.y * __builtin_amdgcn_exp2f(b.x - M) + c.y * __builtin_amdgcn_exp2f(c.x - M) + d.y * __builtin_amdgcn_exp2f(d.x - M);
;                 const float own = wc == 0 ? a.x : wc == 1 ? b.x : wc == 2 ? c.x : d.x;
;                 const float f = __builtin_amdgcn_exp2f(own - M) / tot;
;                 bf16_t* rowp = P + (size_t)(u.r0 + rl) * ldc + u.c0 + wc * 32 + 8 * fq;
; #pragma unroll
;                 for (int bj = 0; bj < 2; ++bj) *(u32x4*)(rowp + bj * HALF) = pack8(acc[ai][bj][m][0] * f, acc[ai][bj][m][1] * f); }
.LBB0_608:
	v_sub_f32_e32 v0, v0, v121
	v_exp_f32_e32 v0, v0
	v_sub_f32_e32 v2, v2, v121
	v_exp_f32_e32 v2, v2
	v_mul_f32_e32 v6, v7, v6
	v_fmac_f32_e32 v6, v5, v120
	v_fmac_f32_e32 v6, v1, v0
	v_fmac_f32_e32 v6, v3, v2
	v_div_scale_f32 v0, s[2:3], v6, v6, v4
	v_rcp_f32_e32 v1, v0
	s_cmp_lt_i32 s64, 1
	v_fma_f32 v2, -v0, v1, 1.0
	v_fmac_f32_e32 v1, v2, v1
	v_div_scale_f32 v2, vcc, v4, v6, v4
	v_mul_f32_e32 v3, v2, v1
	v_fma_f32 v5, -v0, v3, v2
	v_fmac_f32_e32 v3, v5, v1
	v_fma_f32 v0, -v0, v3, v2
	v_div_fmas_f32 v0, v0, v1, v3
	v_div_fixup_f32 v4, v0, v6, v4
	v_lshl_add_u64 v[126:127], v[126:127], 0, s[88:89]
	v_pk_mul_f32 v[0:1], v[104:105], v[4:5] op_sel_hi:[1,0]
	v_pk_mul_f32 v[2:3], v[110:111], v[4:5] op_sel_hi:[1,0]
	v_cvt_pk_bf16_f32 v0, v0, v1
	v_pk_mul_f32 v[104:105], v[116:117], v[4:5] op_sel_hi:[1,0]
	v_cvt_pk_bf16_f32 v1, v2, v3
	v_pk_mul_f32 v[108:109], v[108:109], v[4:5] op_sel_hi:[1,0]
	s_nop 0
	v_cvt_pk_bf16_f32 v2, v108, v109
	v_cvt_pk_bf16_f32 v3, v104, v105
	flat_store_dwordx4 v[126:127], v[0:3]
	v_pk_mul_f32 v[104:105], v[118:119], v[4:5] op_sel_hi:[1,0]
	s_nop 0
	v_pk_mul_f32 v[0:1], v[106:107], v[4:5] op_sel_hi:[1,0]
	v_pk_mul_f32 v[2:3], v[114:115], v[4:5] op_sel_hi:[1,0]
	v_cvt_pk_bf16_f32 v0, v0, v1
	v_pk_mul_f32 v[4:5], v[112:113], v[4:5] op_sel_hi:[1,0]
	v_cvt_pk_bf16_f32 v1, v2, v3
	s_nop 0
	v_cvt_pk_bf16_f32 v2, v4, v5
	v_cvt_pk_bf16_f32 v3, v104, v105
	flat_store_dwordx4 v[126:127], v[0:3] offset:256
	s_nop 1
	v_add_u32_e32 v0, 0, v164
	v_add_u32_e32 v4, 0x20000, v0
	ds_read_b128 v[0:3], v4 offset:16
	ds_read_b128 v[4:7], v4
	s_waitcnt lgkmcnt(0)
	v_max_f32_e32 v104, v2, v2
	v_max_f32_e32 v105, v0, v0
	v_max_f32_e32 v104, v105, v104
	v_max3_f32 v105, v4, v6, v104
	v_sub_f32_e32 v4, v4, v105
	v_exp_f32_e32 v104, v4
	v_sub_f32_e32 v4, v6, v105
	v_exp_f32_e32 v6, v4
	v_mov_b32_e32 v4, v104
	s_cbranch_scc1 .LBB0_613
	s_cmp_lg_u32 s64, 1
	s_mov_b64 s[2:3], -1
	s_cbranch_scc0 .LBB0_611
	v_cndmask_b32_e64 v4, v2, v0, s[8:9]
	v_sub_f32_e32 v4, v4, v105
	v_exp_f32_e32 v4, v4
	s_mov_b64 s[2:3], 0

; __device__ __forceinline__ u32x4 pack8(f32x4 v0, f32x4 v1) { u32x4 w; w.x = cvt_pk_bf16(v0[0], v0[1]); w.y = cvt_pk_bf16(v0[2], v0[3]); w.z = cvt_pk_bf16(v1[0], v1[1]); w.w = cvt_pk_bf16(v1[2], v1[3]); return w; }
;     __device__ __forceinline__ void operator()(Acc& acc, const Unit& u, int wr, int wc, int fr, int fq, PG8_LAS unsigned char* xl) const {
;     ...
;             for (int m = 0; m < 4; ++m) { const int rl = ai * HALF + wr * 64 + m * 16 + fr;
;                 const f32x2 a = X[rl * 4 + 0], b = X[rl * 4 + 1], c = X[rl * 4 + 2], d = X[rl * 4 + 3];
;                 const float M = fmaxf(fmaxf(a.x, b.x), fmaxf(c.x, d.x));
;                 const float tot = a.y * __builtin_amdgcn_exp2f(a.x - M) + b.y * __builtin_amdgcn_exp2f(b.x - M) + c.y * __builtin_amdgcn_exp2f(c.x - M) + d.y * __builtin_amdgcn_exp2f(d.x - M);
;                 const float own = wc == 0 ? a.x : wc == 1 ? b.x : wc == 2 ? c.x : d.x;
;                 const float f = __builtin_amdgcn_exp2f(own - M) / tot;
;                 bf16_t* rowp = P + (size_t)(u.r0 + rl) * ldc + u.c0 + wc * 32 + 8 * fq;
; #pragma unroll
;                 for (int bj = 0; bj < 2; ++bj) *(u32x4*)(rowp + bj * HALF) = pack8(acc[ai][bj][m][0] * f, acc[ai][bj][m][1] * f); }
.LBB0_613:
	v_sub_f32_e32 v0, v0, v105
	v_exp_f32_e32 v0, v0
	v_sub_f32_e32 v2, v2, v105
	v_exp_f32_e32 v2, v2
	v_mul_f32_e32 v6, v7, v6
	v_fmac_f32_e32 v6, v5, v104
	v_fmac_f32_e32 v6, v1, v0
	v_fmac_f32_e32 v6, v3, v2
	v_div_scale_f32 v0, s[2:3], v6, v6, v4
	v_rcp_f32_e32 v1, v0
	s_cmp_lt_i32 s64, 1
	v_fma_f32 v2, -v0, v1, 1.0
	v_fmac_f32_e32 v1, v2, v1
	v_div_scale_f32 v2, vcc, v4, v6, v4
	v_mul_f32_e32 v3, v2, v1
	v_fma_f32 v5, -v0, v3, v2
	v_fmac_f32_e32 v3, v5, v1
	v_fma_f32 v0, -v0, v3, v2
	v_div_fmas_f32 v0, v0, v1, v3
	v_div_fixup_f32 v4, v0, v6, v4
	v_lshl_add_u64 v[126:127], v[126:127], 0, s[88:89]
	v_pk_mul_f32 v[0:1], v[88:89], v[4:5] op_sel_hi:[1,0]
	v_pk_mul_f32 v[2:3], v[94:95], v[4:5] op_sel_hi:[1,0]
	v_cvt_pk_bf16_f32 v0, v0, v1
	v_pk_mul_f32 v[88:89], v[100:101], v[4:5] op_sel_hi:[1,0]
	v_cvt_pk_bf16_f32 v1, v2, v3
	v_pk_mul_f32 v[92:93], v[92:93], v[4:5] op_sel_hi:[1,0]
	s_nop 0
	v_cvt_pk_bf16_f32 v2, v92, v93
	v_cvt_pk_bf16_f32 v3, v88, v89
	flat_store_dwordx4 v[126:127], v[0:3]
	v_pk_mul_f32 v[88:89], v[102:103], v[4:5] op_sel_hi:[1,0]
	s_nop 0
	v_pk_mul_f32 v[0:1], v[90:91], v[4:5] op_sel_hi:[1,0]
	v_pk_mul_f32 v[2:3], v[98:99], v[4:5] op_sel_hi:[1,0]
	v_cvt_pk_bf16_f32 v0, v0, v1
	v_pk_mul_f32 v[4:5], v[96:97], v[4:5] op_sel_hi:[1,0]
	v_cvt_pk_bf16_f32 v1, v2, v3
	s_nop 0
	v_cvt_pk_bf16_f32 v2, v4, v5
	v_cvt_pk_bf16_f32 v3, v88, v89
	flat_store_dwordx4 v[126:127], v[0:3] offset:256
	s_nop 1
	v_add_u32_e32 v0, 0, v167
	v_add_u32_e32 v4, 0x20000, v0
	ds_read_b128 v[0:3], v4 offset:16
	ds_read_b128 v[4:7], v4
	s_waitcnt lgkmcnt(0)
	v_max_f32_e32 v88, v2, v2
	v_max_f32_e32 v89, v0, v0
	v_max_f32_e32 v88, v89, v88
	v_max3_f32 v89, v4, v6, v88
	v_sub_f32_e32 v4, v4, v89
	v_exp_f32_e32 v88, v4
	v_sub_f32_e32 v4, v6, v89
	v_exp_f32_e32 v6, v4
	v_mov_b32_e32 v4, v88
	s_cbranch_scc1 .LBB0_618
	s_cmp_lg_u32 s64, 1
	s_mov_b64 s[2:3], -1
	s_cbranch_scc0 .LBB0_616
	v_cndmask_b32_e64 v4, v2, v0, s[8:9]
	v_sub_f32_e32 v4, v4, v89
	v_exp_f32_e32 v4, v4
	s_mov_b64 s[2:3], 0

; __device__ __forceinline__ u32x4 pack8(f32x4 v0, f32x4 v1) { u32x4 w; w.x = cvt_pk_bf16(v0[0], v0[1]); w.y = cvt_pk_bf16(v0[2], v0[3]); w.z = cvt_pk_bf16(v1[0], v1[1]); w.w = cvt_pk_bf16(v1[2], v1[3]); return w; }
;     __device__ __forceinline__ void operator()(Acc& acc, const Unit& u, int wr, int wc, int fr, int fq, PG8_LAS unsigned char* xl) const {
;     ...
;             for (int m = 0; m < 4; ++m) { const int rl = ai * HALF + wr * 64 + m * 16 + fr;
;                 const f32x2 a = X[rl * 4 + 0], b = X[rl * 4 + 1], c = X[rl * 4 + 2], d = X[rl * 4 + 3];
;                 const float M = fmaxf(fmaxf(a.x, b.x), fmaxf(c.x, d.x));
;                 const float tot = a.y * __builtin_amdgcn_exp2f(a.x - M) + b.y * __builtin_amdgcn_exp2f(b.x - M) + c.y * __builtin_amdgcn_exp2f(c.x - M) + d.y * __builtin_amdgcn_exp2f(d.x - M);
;                 const float own = wc == 0 ? a.x : wc == 1 ? b.x : wc == 2 ? c.x : d.x;
;                 const float f = __builtin_amdgcn_exp2f(own - M) / tot;
;                 bf16_t* rowp = P + (size_t)(u.r0 + rl) * ldc + u.c0 + wc * 32 + 8 * fq;
; #pragma unroll
;                 for (int bj = 0; bj < 2; ++bj) *(u32x4*)(rowp + bj * HALF) = pack8(acc[ai][bj][m][0] * f, acc[ai][bj][m][1] * f); }
.LBB0_618:
	v_sub_f32_e32 v0, v0, v89
	v_exp_f32_e32 v0, v0
	v_sub_f32_e32 v2, v2, v89
	v_exp_f32_e32 v2, v2
	v_mul_f32_e32 v6, v7, v6
	v_fmac_f32_e32 v6, v5, v88
	v_fmac_f32_e32 v6, v1, v0
	v_fmac_f32_e32 v6, v3, v2
	v_div_scale_f32 v0, s[2:3], v6, v6, v4
	v_rcp_f32_e32 v1, v0
	s_cmp_lt_i32 s64, 1
	v_fma_f32 v2, -v0, v1, 1.0
	v_fmac_f32_e32 v1, v2, v1
	v_div_scale_f32 v2, vcc, v4, v6, v4
	v_mul_f32_e32 v3, v2, v1
	v_fma_f32 v5, -v0, v3, v2
	v_fmac_f32_e32 v3, v5, v1
	v_fma_f32 v0, -v0, v3, v2
	v_div_fmas_f32 v0, v0, v1, v3
	v_div_fixup_f32 v4, v0, v6, v4
	v_lshl_add_u64 v[126:127], v[126:127], 0, s[88:89]
	v_pk_mul_f32 v[0:1], v[72:73], v[4:5] op_sel_hi:[1,0]
	v_pk_mul_f32 v[2:3], v[78:79], v[4:5] op_sel_hi:[1,0]
	v_cvt_pk_bf16_f32 v0, v0, v1
	v_pk_mul_f32 v[72:73], v[84:85], v[4:5] op_sel_hi:[1,0]
	v_cvt_pk_bf16_f32 v1, v2, v3
	v_pk_mul_f32 v[76:77], v[76:77], v[4:5] op_sel_hi:[1,0]
	s_nop 0
	v_cvt_pk_bf16_f32 v2, v76, v77
	v_cvt_pk_bf16_f32 v3, v72, v73
	flat_store_dwordx4 v[126:127], v[0:3]
	v_pk_mul_f32 v[72:73], v[86:87], v[4:5] op_sel_hi:[1,0]
	s_nop 0
	v_pk_mul_f32 v[0:1], v[74:75], v[4:5] op_sel_hi:[1,0]
	v_pk_mul_f32 v[2:3], v[82:83], v[4:5] op_sel_hi:[1,0]
	v_cvt_pk_bf16_f32 v0, v0, v1
	v_pk_mul_f32 v[4:5], v[80:81], v[4:5] op_sel_hi:[1,0]
	v_cvt_pk_bf16_f32 v1, v2, v3
	s_nop 0
	v_cvt_pk_bf16_f32 v2, v4, v5
	v_cvt_pk_bf16_f32 v3, v72, v73
	flat_store_dwordx4 v[126:127], v[0:3] offset:256
	s_nop 1
	v_add_u32_e32 v0, 0, v170
	v_add_u32_e32 v4, 0x20000, v0
	ds_read_b128 v[0:3], v4 offset:16
	ds_read_b128 v[4:7], v4
	s_waitcnt lgkmcnt(0)
	v_max_f32_e32 v72, v2, v2
	v_max_f32_e32 v73, v0, v0
	v_max_f32_e32 v72, v73, v72
	v_max3_f32 v73, v4, v6, v72
	v_sub_f32_e32 v4, v4, v73
	v_exp_f32_e32 v72, v4
	v_sub_f32_e32 v4, v6, v73
	v_exp_f32_e32 v6, v4
	v_mov_b32_e32 v4, v72
	s_cbranch_scc1 .LBB0_623
	s_cmp_lg_u32 s64, 1
	s_mov_b64 s[2:3], -1
	s_cbranch_scc0 .LBB0_621
	v_cndmask_b32_e64 v4, v2, v0, s[8:9]
	v_sub_f32_e32 v4, v4, v73
	v_exp_f32_e32 v4, v4
	s_mov_b64 s[2:3], 0

; __device__ __forceinline__ u32x4 pack8(f32x4 v0, f32x4 v1) { u32x4 w; w.x = cvt_pk_bf16(v0[0], v0[1]); w.y = cvt_pk_bf16(v0[2], v0[3]); w.z = cvt_pk_bf16(v1[0], v1[1]); w.w = cvt_pk_bf16(v1[2], v1[3]); return w; }
;     __device__ __forceinline__ void operator()(Acc& acc, const Unit& u, int wr, int wc, int fr, int fq, PG8_LAS unsigned char* xl) const {
;     ...
;             for (int m = 0; m < 4; ++m) { const int rl = ai * HALF + wr * 64 + m * 16 + fr;
;                 const f32x2 a = X[rl * 4 + 0], b = X[rl * 4 + 1], c = X[rl * 4 + 2], d = X[rl * 4 + 3];
;                 const float M = fmaxf(fmaxf(a.x, b.x), fmaxf(c.x, d.x));
;                 const float tot = a.y * __builtin_amdgcn_exp2f(a.x - M) + b.y * __builtin_amdgcn_exp2f(b.x - M) + c.y * __builtin_amdgcn_exp2f(c.x - M) + d.y * __builtin_amdgcn_exp2f(d.x - M);
;                 const float own = wc == 0 ? a.x : wc == 1 ? b.x : wc == 2 ? c.x : d.x;
;                 const float f = __builtin_amdgcn_exp2f(own - M) / tot;
;                 bf16_t* rowp = P + (size_t)(u.r0 + rl) * ldc + u.c0 + wc * 32 + 8 * fq;
; #pragma unroll
;                 for (int bj = 0; bj < 2; ++bj) *(u32x4*)(rowp + bj * HALF) = pack8(acc[ai][bj][m][0] * f, acc[ai][bj][m][1] * f); }
.LBB0_623:
	v_sub_f32_e32 v0, v0, v73
	v_exp_f32_e32 v0, v0
	v_sub_f32_e32 v2, v2, v73
	v_exp_f32_e32 v2, v2
	v_mul_f32_e32 v6, v7, v6
	v_fmac_f32_e32 v6, v5, v72
	v_fmac_f32_e32 v6, v1, v0
	v_fmac_f32_e32 v6, v3, v2
	v_div_scale_f32 v0, s[2:3], v6, v6, v4
	v_rcp_f32_e32 v1, v0
	s_cmp_lt_i32 s64, 1
	v_fma_f32 v2, -v0, v1, 1.0
	v_fmac_f32_e32 v1, v2, v1
	v_div_scale_f32 v2, vcc, v4, v6, v4
	v_mul_f32_e32 v3, v2, v1
	v_fma_f32 v5, -v0, v3, v2
	v_fmac_f32_e32 v3, v5, v1
	v_fma_f32 v0, -v0, v3, v2
	v_div_fmas_f32 v0, v0, v1, v3
	v_div_fixup_f32 v4, v0, v6, v4
	v_lshl_add_u64 v[126:127], v[126:127], 0, s[90:91]
	v_pk_mul_f32 v[0:1], v[56:57], v[4:5] op_sel_hi:[1,0]
	v_pk_mul_f32 v[2:3], v[62:63], v[4:5] op_sel_hi:[1,0]
	v_cvt_pk_bf16_f32 v0, v0, v1
	v_pk_mul_f32 v[56:57], v[68:69], v[4:5] op_sel_hi:[1,0]
	v_cvt_pk_bf16_f32 v1, v2, v3
	v_pk_mul_f32 v[60:61], v[60:61], v[4:5] op_sel_hi:[1,0]
	s_nop 0
	v_cvt_pk_bf16_f32 v2, v60, v61
	v_cvt_pk_bf16_f32 v3, v56, v57
	flat_store_dwordx4 v[126:127], v[0:3]
	v_pk_mul_f32 v[56:57], v[70:71], v[4:5] op_sel_hi:[1,0]
	s_nop 0
	v_pk_mul_f32 v[0:1], v[58:59], v[4:5] op_sel_hi:[1,0]
	v_pk_mul_f32 v[2:3], v[66:67], v[4:5] op_sel_hi:[1,0]
	v_cvt_pk_bf16_f32 v0, v0, v1
	v_pk_mul_f32 v[4:5], v[64:65], v[4:5] op_sel_hi:[1,0]
	v_cvt_pk_bf16_f32 v1, v2, v3
	s_nop 0
	v_cvt_pk_bf16_f32 v2, v4, v5
	v_cvt_pk_bf16_f32 v3, v56, v57
	flat_store_dwordx4 v[126:127], v[0:3] offset:256
	s_nop 1
	v_add_u32_e32 v0, 0, v173
	v_add_u32_e32 v4, 0x20000, v0
	ds_read_b128 v[0:3], v4 offset:16
	ds_read_b128 v[4:7], v4
	s_waitcnt lgkmcnt(0)
	v_max_f32_e32 v56, v2, v2
	v_max_f32_e32 v57, v0, v0
	v_max_f32_e32 v56, v57, v56
	v_max3_f32 v57, v4, v6, v56
	v_sub_f32_e32 v4, v4, v57
	v_exp_f32_e32 v56, v4
	v_sub_f32_e32 v4, v6, v57
	v_exp_f32_e32 v6, v4
	v_mov_b32_e32 v4, v56
	s_cbranch_scc1 .LBB0_628
	s_cmp_lg_u32 s64, 1
	s_mov_b64 s[2:3], -1
	s_cbranch_scc0 .LBB0_626
	v_cndmask_b32_e64 v4, v2, v0, s[8:9]
	v_sub_f32_e32 v4, v4, v57
	v_exp_f32_e32 v4, v4
	s_mov_b64 s[2:3], 0

; __device__ __forceinline__ u32x4 pack8(f32x4 v0, f32x4 v1) { u32x4 w; w.x = cvt_pk_bf16(v0[0], v0[1]); w.y = cvt_pk_bf16(v0[2], v0[3]); w.z = cvt_pk_bf16(v1[0], v1[1]); w.w = cvt_pk_bf16(v1[2], v1[3]); return w; }
;     __device__ __forceinline__ void operator()(Acc& acc, const Unit& u, int wr, int wc, int fr, int fq, PG8_LAS unsigned char* xl) const {
;     ...
;             for (int m = 0; m < 4; ++m) { const int rl = ai * HALF + wr * 64 + m * 16 + fr;
;                 const f32x2 a = X[rl * 4 + 0], b = X[rl * 4 + 1], c = X[rl * 4 + 2], d = X[rl * 4 + 3];
;                 const float M = fmaxf(fmaxf(a.x, b.x), fmaxf(c.x, d.x));
;                 const float tot = a.y * __builtin_amdgcn_exp2f(a.x - M) + b.y * __builtin_amdgcn_exp2f(b.x - M) + c.y * __builtin_amdgcn_exp2f(c.x - M) + d.y * __builtin_amdgcn_exp2f(d.x - M);
;                 const float own = wc == 0 ? a.x : wc == 1 ? b.x : wc == 2 ? c.x : d.x;
;                 const float f = __builtin_amdgcn_exp2f(own - M) / tot;
;                 bf16_t* rowp = P + (size_t)(u.r0 + rl) * ldc + u.c0 + wc * 32 + 8 * fq;
; #pragma unroll
;                 for (int bj = 0; bj < 2; ++bj) *(u32x4*)(rowp + bj * HALF) = pack8(acc[ai][bj][m][0] * f, acc[ai][bj][m][1] * f); }
.LBB0_628:
	v_sub_f32_e32 v0, v0, v57
	v_exp_f32_e32 v0, v0
	v_sub_f32_e32 v2, v2, v57
	v_exp_f32_e32 v2, v2
	v_mul_f32_e32 v6, v7, v6
	v_fmac_f32_e32 v6, v5, v56
	v_fmac_f32_e32 v6, v1, v0
	v_fmac_f32_e32 v6, v3, v2
	v_div_scale_f32 v0, s[2:3], v6, v6, v4
	v_rcp_f32_e32 v1, v0
	s_cmp_lt_i32 s64, 1
	v_fma_f32 v2, -v0, v1, 1.0
	v_fmac_f32_e32 v1, v2, v1
	v_div_scale_f32 v2, vcc, v4, v6, v4
	v_mul_f32_e32 v3, v2, v1
	v_fma_f32 v5, -v0, v3, v2
	v_fmac_f32_e32 v3, v5, v1
	v_fma_f32 v0, -v0, v3, v2
	v_div_fmas_f32 v0, v0, v1, v3
	v_div_fixup_f32 v4, v0, v6, v4
	v_lshl_add_u64 v[126:127], v[126:127], 0, s[88:89]
	v_pk_mul_f32 v[0:1], v[40:41], v[4:5] op_sel_hi:[1,0]
	v_pk_mul_f32 v[2:3], v[46:47], v[4:5] op_sel_hi:[1,0]
	v_cvt_pk_bf16_f32 v0, v0, v1
	v_pk_mul_f32 v[40:41], v[52:53], v[4:5] op_sel_hi:[1,0]
	v_cvt_pk_bf16_f32 v1, v2, v3
	v_pk_mul_f32 v[44:45], v[44:45], v[4:5] op_sel_hi:[1,0]
	s_nop 0
	v_cvt_pk_bf16_f32 v2, v44, v45
	v_cvt_pk_bf16_f32 v3, v40, v41
	flat_store_dwordx4 v[126:127], v[0:3]
	v_pk_mul_f32 v[40:41], v[54:55], v[4:5] op_sel_hi:[1,0]
	s_nop 0
	v_pk_mul_f32 v[0:1], v[42:43], v[4:5] op_sel_hi:[1,0]
	v_pk_mul_f32 v[2:3], v[50:51], v[4:5] op_sel_hi:[1,0]
	v_cvt_pk_bf16_f32 v0, v0, v1
	v_pk_mul_f32 v[4:5], v[48:49], v[4:5] op_sel_hi:[1,0]
	v_cvt_pk_bf16_f32 v1, v2, v3
	s_nop 0
	v_cvt_pk_bf16_f32 v2, v4, v5
	v_cvt_pk_bf16_f32 v3, v40, v41
	flat_store_dwordx4 v[126:127], v[0:3] offset:256
	s_nop 1
	v_add_u32_e32 v0, 0, v176
	v_add_u32_e32 v4, 0x20000, v0
	ds_read_b128 v[0:3], v4 offset:16
	ds_read_b128 v[4:7], v4
	s_waitcnt lgkmcnt(0)
	v_max_f32_e32 v40, v2, v2
	v_max_f32_e32 v41, v0, v0
	v_max_f32_e32 v40, v41, v40
	v_max3_f32 v41, v4, v6, v40
	v_sub_f32_e32 v4, v4, v41
	v_exp_f32_e32 v40, v4
	v_sub_f32_e32 v4, v6, v41
	v_exp_f32_e32 v6, v4
	v_mov_b32_e32 v4, v40
	s_cbranch_scc1 .LBB0_633
	s_cmp_lg_u32 s64, 1
	s_mov_b64 s[2:3], -1
	s_cbranch_scc0 .LBB0_631
	v_cndmask_b32_e64 v4, v2, v0, s[8:9]
	v_sub_f32_e32 v4, v4, v41
	v_exp_f32_e32 v4, v4
	s_mov_b64 s[2:3], 0

; __device__ __forceinline__ u32x4 pack8(f32x4 v0, f32x4 v1) { u32x4 w; w.x = cvt_pk_bf16(v0[0], v0[1]); w.y = cvt_pk_bf16(v0[2], v0[3]); w.z = cvt_pk_bf16(v1[0], v1[1]); w.w = cvt_pk_bf16(v1[2], v1[3]); return w; }
;     __device__ __forceinline__ void operator()(Acc& acc, const Unit& u, int wr, int wc, int fr, int fq, PG8_LAS unsigned char* xl) const {
;     ...
;             for (int m = 0; m < 4; ++m) { const int rl = ai * HALF + wr * 64 + m * 16 + fr;
;                 const f32x2 a = X[rl * 4 + 0], b = X[rl * 4 + 1], c = X[rl * 4 + 2], d = X[rl * 4 + 3];
;                 const float M = fmaxf(fmaxf(a.x, b.x), fmaxf(c.x, d.x));
;                 const float tot = a.y * __builtin_amdgcn_exp2f(a.x - M) + b.y * __builtin_amdgcn_exp2f(b.x - M) + c.y * __builtin_amdgcn_exp2f(c.x - M) + d.y * __builtin_amdgcn_exp2f(d.x - M);
;                 const float own = wc == 0 ? a.x : wc == 1 ? b.x : wc == 2 ? c.x : d.x;
;                 const float f = __builtin_amdgcn_exp2f(own - M) / tot;
;                 bf16_t* rowp = P + (size_t)(u.r0 + rl) * ldc + u.c0 + wc * 32 + 8 * fq;
; #pragma unroll
;                 for (int bj = 0; bj < 2; ++bj) *(u32x4*)(rowp + bj * HALF) = pack8(acc[ai][bj][m][0] * f, acc[ai][bj][m][1] * f); }
.LBB0_633:
	v_sub_f32_e32 v0, v0, v41
	v_exp_f32_e32 v0, v0
	v_sub_f32_e32 v2, v2, v41
	v_exp_f32_e32 v2, v2
	v_mul_f32_e32 v6, v7, v6
	v_fmac_f32_e32 v6, v5, v40
	v_fmac_f32_e32 v6, v1, v0
	v_fmac_f32_e32 v6, v3, v2
	v_div_scale_f32 v0, s[2:3], v6, v6, v4
	v_rcp_f32_e32 v1, v0
	s_cmp_lt_i32 s64, 1
	v_fma_f32 v2, -v0, v1, 1.0
	v_fmac_f32_e32 v1, v2, v1
	v_div_scale_f32 v2, vcc, v4, v6, v4
	v_mul_f32_e32 v3, v2, v1
	v_fma_f32 v5, -v0, v3, v2
	v_fmac_f32_e32 v3, v5, v1
	v_fma_f32 v0, -v0, v3, v2
	v_div_fmas_f32 v0, v0, v1, v3
	v_div_fixup_f32 v4, v0, v6, v4
	v_lshl_add_u64 v[126:127], v[126:127], 0, s[88:89]
	v_pk_mul_f32 v[0:1], v[24:25], v[4:5] op_sel_hi:[1,0]
	v_pk_mul_f32 v[2:3], v[30:31], v[4:5] op_sel_hi:[1,0]
	v_cvt_pk_bf16_f32 v0, v0, v1
	v_pk_mul_f32 v[24:25], v[36:37], v[4:5] op_sel_hi:[1,0]
	v_cvt_pk_bf16_f32 v1, v2, v3
	v_pk_mul_f32 v[28:29], v[28:29], v[4:5] op_sel_hi:[1,0]
	s_nop 0
	v_cvt_pk_bf16_f32 v2, v28, v29
	v_cvt_pk_bf16_f32 v3, v24, v25
	flat_store_dwordx4 v[126:127], v[0:3]
	v_pk_mul_f32 v[24:25], v[38:39], v[4:5] op_sel_hi:[1,0]
	s_nop 0
	v_pk_mul_f32 v[0:1], v[26:27], v[4:5] op_sel_hi:[1,0]
	v_pk_mul_f32 v[2:3], v[34:35], v[4:5] op_sel_hi:[1,0]
	v_cvt_pk_bf16_f32 v0, v0, v1
	v_pk_mul_f32 v[4:5], v[32:33], v[4:5] op_sel_hi:[1,0]
	v_cvt_pk_bf16_f32 v1, v2, v3
	s_nop 0
	v_cvt_pk_bf16_f32 v2, v4, v5
	v_cvt_pk_bf16_f32 v3, v24, v25
	flat_store_dwordx4 v[126:127], v[0:3] offset:256
	s_nop 1
	v_add_u32_e32 v0, 0, v180
	v_add_u32_e32 v0, 0x20000, v0
	ds_read_b128 v[4:7], v0 offset:16
	ds_read_b128 v[0:3], v0
	s_waitcnt lgkmcnt(0)
	v_max_f32_e32 v24, v6, v6
	v_max_f32_e32 v25, v4, v4
	v_max_f32_e32 v24, v25, v24
	v_max3_f32 v26, v0, v2, v24
	v_sub_f32_e32 v0, v0, v26
	v_exp_f32_e32 v24, v0
	v_sub_f32_e32 v0, v2, v26
	v_exp_f32_e32 v25, v0
	v_mov_b32_e32 v0, v24
	s_cbranch_scc1 .LBB0_638
	s_cmp_lg_u32 s64, 1
	s_mov_b64 s[2:3], -1
	s_cbranch_scc0 .LBB0_636
	v_cndmask_b32_e64 v0, v6, v4, s[8:9]
	v_sub_f32_e32 v0, v0, v26
	v_exp_f32_e32 v0, v0
	s_mov_b64 s[2:3], 0

; __device__ __forceinline__ u32x4 pack8(f32x4 v0, f32x4 v1) { u32x4 w; w.x = cvt_pk_bf16(v0[0], v0[1]); w.y = cvt_pk_bf16(v0[2], v0[3]); w.z = cvt_pk_bf16(v1[0], v1[1]); w.w = cvt_pk_bf16(v1[2], v1[3]); return w; }
;     __device__ __forceinline__ void operator()(Acc& acc, const Unit& u, int wr, int wc, int fr, int fq, PG8_LAS unsigned char* xl) const {
;     ...
;                 const f32x2 a = X[rl * 4 + 0], b = X[rl * 4 + 1], c = X[rl * 4 + 2], d = X[rl * 4 + 3];
;                 const float M = fmaxf(fmaxf(a.x, b.x), fmaxf(c.x, d.x));
;                 const float tot = a.y * __builtin_amdgcn_exp2f(a.x - M) + b.y * __builtin_amdgcn_exp2f(b.x - M) + c.y * __builtin_amdgcn_exp2f(c.x - M) + d.y * __builtin_amdgcn_exp2f(d.x - M);
;                 const float own = wc == 0 ? a.x : wc == 1 ? b.x : wc == 2 ? c.x : d.x;
;                 const float f = __builtin_amdgcn_exp2f(own - M) / tot;
;                 bf16_t* rowp = P + (size_t)(u.r0 + rl) * ldc + u.c0 + wc * 32 + 8 * fq;
; #pragma unroll
;                 for (int bj = 0; bj < 2; ++bj) *(u32x4*)(rowp + bj * HALF) = pack8(acc[ai][bj][m][0] * f, acc[ai][bj][m][1] * f); }
.LBB0_638:
	v_sub_f32_e32 v2, v6, v26
	v_exp_f32_e32 v28, v2
	v_sub_f32_e32 v2, v4, v26
	v_exp_f32_e32 v29, v2
	v_mov_b32_e32 v2, v1
	v_mov_b32_e32 v4, v7
	v_pk_mul_f32 v[2:3], v[2:3], v[24:25]
	v_pk_mul_f32 v[4:5], v[4:5], v[28:29]
	v_add_f32_e32 v1, v2, v3
	v_add_f32_e32 v1, v5, v1
	v_add_f32_e32 v1, v4, v1
	v_div_scale_f32 v2, s[2:3], v1, v1, v0
	v_rcp_f32_e32 v3, v2
	s_mov_b64 s[2:3], -1
	v_fma_f32 v4, -v2, v3, 1.0
	v_fmac_f32_e32 v3, v4, v3
	v_div_scale_f32 v4, vcc, v0, v1, v0
	v_mul_f32_e32 v5, v4, v3
	v_fma_f32 v6, -v2, v5, v4
	v_fmac_f32_e32 v5, v6, v3
	v_fma_f32 v2, -v2, v5, v4
	v_div_fmas_f32 v2, v2, v3, v5
	v_div_fixup_f32 v4, v2, v1, v0
	v_lshl_add_u64 v[126:127], v[126:127], 0, s[88:89]
	v_pk_mul_f32 v[2:3], v[14:15], v[4:5] op_sel_hi:[1,0]
	v_pk_mul_f32 v[0:1], v[8:9], v[4:5] op_sel_hi:[1,0]
	v_pk_mul_f32 v[8:9], v[20:21], v[4:5] op_sel_hi:[1,0]
	v_pk_mul_f32 v[12:13], v[12:13], v[4:5] op_sel_hi:[1,0]
	v_cvt_pk_bf16_f32 v0, v0, v1
	v_cvt_pk_bf16_f32 v1, v2, v3
	s_andn2_b64 vcc, exec, s[10:11]
	v_cvt_pk_bf16_f32 v2, v12, v13
	v_cvt_pk_bf16_f32 v3, v8, v9
	flat_store_dwordx4 v[126:127], v[0:3]
	v_pk_mul_f32 v[8:9], v[22:23], v[4:5] op_sel_hi:[1,0]
	s_nop 0
	v_pk_mul_f32 v[2:3], v[18:19], v[4:5] op_sel_hi:[1,0]
	v_pk_mul_f32 v[0:1], v[10:11], v[4:5] op_sel_hi:[1,0]
	v_pk_mul_f32 v[4:5], v[16:17], v[4:5] op_sel_hi:[1,0]
	v_cvt_pk_bf16_f32 v0, v0, v1
	v_cvt_pk_bf16_f32 v1, v2, v3
	s_nop 0
	v_cvt_pk_bf16_f32 v2, v4, v5
	v_cvt_pk_bf16_f32 v3, v8, v9
	flat_store_dwordx4 v[126:127], v[0:3] offset:256
	s_cbranch_vccnz .LBB0_569
	s_andn2_b64 vcc, exec, s[14:15]
	s_cbranch_vccnz .LBB0_568
	s_barrier
	s_branch .LBB0_568
